# code placement: K-loop heads at a 64-byte boundary + 8 bytes (same 8-byte phase as the aligned variant, different cache-line offset)
# speedup vs baseline: 1.0008x; 1.0008x over previous
; DI void gemm_stream2(const bf16_t* __restrict__ A, int lda, const bf16_t* __restrict__ Bt, int ldb, int K, int m0, int n0, ...
;     ...
;     for (int kt = 0; kt < nk; ++kt) {
;         const bool pf = (kt + 2 < nk) || has_next, more = (kt + 1 < nk) || has_next;
; DI void zero_acc(f32x4 (&acc)[4][4]) {
; #pragma unroll
;     for (int i = 0; i < 4; ++i)
; #pragma unroll
;         for (int j = 0; j < 4; ++j) acc[i][j] = (f32x4){0.f, 0.f, 0.f, 0.f};
; }
.Lgu_nonext:
	v_mov_b64_e32 v[24:25], 0
	v_mov_b64_e32 v[26:27], 0
	v_mov_b64_e32 v[28:29], 0
	v_mov_b64_e32 v[30:31], 0
	v_mov_b64_e32 v[32:33], 0
	v_mov_b64_e32 v[34:35], 0
	v_mov_b64_e32 v[36:37], 0
	v_mov_b64_e32 v[38:39], 0
	v_mov_b64_e32 v[40:41], 0
	v_mov_b64_e32 v[42:43], 0
	v_mov_b64_e32 v[44:45], 0
	v_mov_b64_e32 v[46:47], 0
	v_mov_b64_e32 v[48:49], 0
	v_mov_b64_e32 v[50:51], 0
	v_mov_b64_e32 v[52:53], 0
	v_mov_b64_e32 v[54:55], 0
	v_mov_b64_e32 v[56:57], 0
	v_mov_b64_e32 v[58:59], 0
	v_mov_b64_e32 v[60:61], 0
	v_mov_b64_e32 v[62:63], 0
	v_mov_b64_e32 v[64:65], 0
	v_mov_b64_e32 v[66:67], 0
	v_mov_b64_e32 v[68:69], 0
	v_mov_b64_e32 v[70:71], 0
	v_mov_b64_e32 v[72:73], 0
	v_mov_b64_e32 v[74:75], 0
	v_mov_b64_e32 v[76:77], 0
	v_mov_b64_e32 v[78:79], 0
	v_mov_b64_e32 v[80:81], 0
	v_mov_b64_e32 v[82:83], 0
	v_mov_b64_e32 v[84:85], 0
	v_mov_b64_e32 v[86:87], 0
	v_mov_b64_e32 v[88:89], 0
	v_mov_b64_e32 v[90:91], 0
	v_mov_b64_e32 v[92:93], 0
	v_mov_b64_e32 v[94:95], 0
	v_mov_b64_e32 v[96:97], 0
	v_mov_b64_e32 v[98:99], 0
	v_mov_b64_e32 v[100:101], 0
	v_mov_b64_e32 v[102:103], 0
	v_mov_b64_e32 v[104:105], 0
	v_mov_b64_e32 v[106:107], 0
	v_mov_b64_e32 v[108:109], 0
	v_mov_b64_e32 v[110:111], 0
	v_mov_b64_e32 v[112:113], 0
	v_mov_b64_e32 v[114:115], 0
	v_mov_b64_e32 v[116:117], 0
	v_mov_b64_e32 v[118:119], 0
	v_mov_b64_e32 v[120:121], 0
	v_mov_b64_e32 v[122:123], 0
	v_mov_b64_e32 v[124:125], 0
	v_mov_b64_e32 v[126:127], 0
	v_mov_b64_e32 v[128:129], 0
	v_mov_b64_e32 v[130:131], 0
	v_mov_b64_e32 v[132:133], 0
	v_mov_b64_e32 v[134:135], 0
	v_mov_b64_e32 v[136:137], 0
	v_mov_b64_e32 v[138:139], 0
	v_mov_b64_e32 v[140:141], 0
	v_mov_b64_e32 v[142:143], 0
	v_mov_b64_e32 v[144:145], 0
	v_mov_b64_e32 v[146:147], 0
	v_mov_b64_e32 v[148:149], 0
	v_mov_b64_e32 v[150:151], 0
	s_add_u32 s0, s54, 7
	.p2alignl 6, 3212836864
	s_nop 0
	s_nop 0

; DI void gemm_stream2(const bf16_t* __restrict__ A, int lda, const bf16_t* __restrict__ Bt, int ldb, int K, int m0, int n0, ...
;     ...
;     for (int kt = 0; kt < nk; ++kt) {
;         const bool pf = (kt + 2 < nk) || has_next, more = (kt + 1 < nk) || has_next;
; DI void zero_acc(f32x4 (&acc)[4][4]) {
; #pragma unroll
;     for (int i = 0; i < 4; ++i)
; #pragma unroll
;         for (int j = 0; j < 4; ++j) acc[i][j] = (f32x4){0.f, 0.f, 0.f, 0.f};
; }
.Lgyd_nx_done:
	v_mov_b64_e32 v[24:25], 0
	v_mov_b64_e32 v[26:27], 0
	v_mov_b64_e32 v[28:29], 0
	v_mov_b64_e32 v[30:31], 0
	v_mov_b64_e32 v[32:33], 0
	v_mov_b64_e32 v[34:35], 0
	v_mov_b64_e32 v[36:37], 0
	v_mov_b64_e32 v[38:39], 0
	v_mov_b64_e32 v[40:41], 0
	v_mov_b64_e32 v[42:43], 0
	v_mov_b64_e32 v[44:45], 0
	v_mov_b64_e32 v[46:47], 0
	v_mov_b64_e32 v[48:49], 0
	v_mov_b64_e32 v[50:51], 0
	v_mov_b64_e32 v[52:53], 0
	v_mov_b64_e32 v[54:55], 0
	v_mov_b64_e32 v[56:57], 0
	v_mov_b64_e32 v[58:59], 0
	v_mov_b64_e32 v[60:61], 0
	v_mov_b64_e32 v[62:63], 0
	v_mov_b64_e32 v[64:65], 0
	v_mov_b64_e32 v[66:67], 0
	v_mov_b64_e32 v[68:69], 0
	v_mov_b64_e32 v[70:71], 0
	v_mov_b64_e32 v[72:73], 0
	v_mov_b64_e32 v[74:75], 0
	v_mov_b64_e32 v[76:77], 0
	v_mov_b64_e32 v[78:79], 0
	v_mov_b64_e32 v[80:81], 0
	v_mov_b64_e32 v[82:83], 0
	v_mov_b64_e32 v[84:85], 0
	v_mov_b64_e32 v[86:87], 0
	v_mov_b64_e32 v[88:89], 0
	v_mov_b64_e32 v[90:91], 0
	v_mov_b64_e32 v[92:93], 0
	v_mov_b64_e32 v[94:95], 0
	v_mov_b64_e32 v[96:97], 0
	v_mov_b64_e32 v[98:99], 0
	v_mov_b64_e32 v[100:101], 0
	v_mov_b64_e32 v[102:103], 0
	v_mov_b64_e32 v[104:105], 0
	v_mov_b64_e32 v[106:107], 0
	v_mov_b64_e32 v[108:109], 0
	v_mov_b64_e32 v[110:111], 0
	v_mov_b64_e32 v[112:113], 0
	v_mov_b64_e32 v[114:115], 0
	v_mov_b64_e32 v[116:117], 0
	v_mov_b64_e32 v[118:119], 0
	v_mov_b64_e32 v[120:121], 0
	v_mov_b64_e32 v[122:123], 0
	v_mov_b64_e32 v[124:125], 0
	v_mov_b64_e32 v[126:127], 0
	v_mov_b64_e32 v[128:129], 0
	v_mov_b64_e32 v[130:131], 0
	v_mov_b64_e32 v[132:133], 0
	v_mov_b64_e32 v[134:135], 0
	v_mov_b64_e32 v[136:137], 0
	v_mov_b64_e32 v[138:139], 0
	v_mov_b64_e32 v[140:141], 0
	v_mov_b64_e32 v[142:143], 0
	v_mov_b64_e32 v[144:145], 0
	v_mov_b64_e32 v[146:147], 0
	v_mov_b64_e32 v[148:149], 0
	v_mov_b64_e32 v[150:151], 0
	s_cmp_eq_u32 s55, 0
	s_cselect_b32 s0, 21, 1
	s_add_u32 s0, s0, s54
	s_cmp_eq_u32 s0, 0
	s_cbranch_scc1 .Lgyd_kdone
	.p2alignl 6, 3212836864
	s_nop 0
	s_nop 0

; DI void gemm_stream2(const bf16_t* __restrict__ A, int lda, const bf16_t* __restrict__ Bt, int ldb, int K, int m0, int n0, ...
;     ...
;     for (int kt = 0; kt < nk; ++kt) {
;         const bool pf = (kt + 2 < nk) || has_next, more = (kt + 1 < nk) || has_next;
; DI void zero_acc(f32x4 (&acc)[4][4]) {
; #pragma unroll
;     for (int i = 0; i < 4; ++i)
; #pragma unroll
;         for (int j = 0; j < 4; ++j) acc[i][j] = (f32x4){0.f, 0.f, 0.f, 0.f};
; }
.Lgyo_nx_done:
	v_mov_b64_e32 v[24:25], 0
	v_mov_b64_e32 v[26:27], 0
	v_mov_b64_e32 v[28:29], 0
	v_mov_b64_e32 v[30:31], 0
	v_mov_b64_e32 v[32:33], 0
	v_mov_b64_e32 v[34:35], 0
	v_mov_b64_e32 v[36:37], 0
	v_mov_b64_e32 v[38:39], 0
	v_mov_b64_e32 v[40:41], 0
	v_mov_b64_e32 v[42:43], 0
	v_mov_b64_e32 v[44:45], 0
	v_mov_b64_e32 v[46:47], 0
	v_mov_b64_e32 v[48:49], 0
	v_mov_b64_e32 v[50:51], 0
	v_mov_b64_e32 v[52:53], 0
	v_mov_b64_e32 v[54:55], 0
	v_mov_b64_e32 v[56:57], 0
	v_mov_b64_e32 v[58:59], 0
	v_mov_b64_e32 v[60:61], 0
	v_mov_b64_e32 v[62:63], 0
	v_mov_b64_e32 v[64:65], 0
	v_mov_b64_e32 v[66:67], 0
	v_mov_b64_e32 v[68:69], 0
	v_mov_b64_e32 v[70:71], 0
	v_mov_b64_e32 v[72:73], 0
	v_mov_b64_e32 v[74:75], 0
	v_mov_b64_e32 v[76:77], 0
	v_mov_b64_e32 v[78:79], 0
	v_mov_b64_e32 v[80:81], 0
	v_mov_b64_e32 v[82:83], 0
	v_mov_b64_e32 v[84:85], 0
	v_mov_b64_e32 v[86:87], 0
	v_mov_b64_e32 v[88:89], 0
	v_mov_b64_e32 v[90:91], 0
	v_mov_b64_e32 v[92:93], 0
	v_mov_b64_e32 v[94:95], 0
	v_mov_b64_e32 v[96:97], 0
	v_mov_b64_e32 v[98:99], 0
	v_mov_b64_e32 v[100:101], 0
	v_mov_b64_e32 v[102:103], 0
	v_mov_b64_e32 v[104:105], 0
	v_mov_b64_e32 v[106:107], 0
	v_mov_b64_e32 v[108:109], 0
	v_mov_b64_e32 v[110:111], 0
	v_mov_b64_e32 v[112:113], 0
	v_mov_b64_e32 v[114:115], 0
	v_mov_b64_e32 v[116:117], 0
	v_mov_b64_e32 v[118:119], 0
	v_mov_b64_e32 v[120:121], 0
	v_mov_b64_e32 v[122:123], 0
	v_mov_b64_e32 v[124:125], 0
	v_mov_b64_e32 v[126:127], 0
	v_mov_b64_e32 v[128:129], 0
	v_mov_b64_e32 v[130:131], 0
	v_mov_b64_e32 v[132:133], 0
	v_mov_b64_e32 v[134:135], 0
	v_mov_b64_e32 v[136:137], 0
	v_mov_b64_e32 v[138:139], 0
	v_mov_b64_e32 v[140:141], 0
	v_mov_b64_e32 v[142:143], 0
	v_mov_b64_e32 v[144:145], 0
	v_mov_b64_e32 v[146:147], 0
	v_mov_b64_e32 v[148:149], 0
	v_mov_b64_e32 v[150:151], 0
	s_cmp_eq_u32 s55, 0
	s_cselect_b32 s0, 7, 0
	s_add_u32 s0, s0, s54
	s_cmp_eq_u32 s0, 0
	s_cbranch_scc1 .Lgyo_kdone
	.p2alignl 6, 3212836864
	s_nop 0
	s_nop 0
